# attention tiles: cross-half row-max exchange via v_permlane32_swap_b32 instead of ds_bpermute LDS round trip (13 sites)
# baseline (speedup 1.0000x reference)
.LBB0_506:
	s_or_b64 exec, exec, s[2:3]
	s_mulk_i32 s16, 0x4800
	v_cmp_lt_i32_e32 vcc, 1, v34
	s_and_saveexec_b64 s[2:3], vcc
	s_xor_b64 s[22:23], exec, s[2:3]
	s_cbranch_execz .LBB0_516
	v_cmp_lt_i32_e32 vcc, 2, v34
	s_and_saveexec_b64 s[2:3], vcc
	s_xor_b64 s[2:3], exec, s[2:3]
	s_cbranch_execz .LBB0_511
	v_add3_u32 v124, s16, v100, v116
	s_setprio 1
	ds_read_b128 v[34:37], v124
	ds_read_b128 v[38:41], v124 offset:16
	ds_read_b128 v[42:45], v124 offset:32
	ds_read_b128 v[46:49], v124 offset:48
	v_cmp_lt_i32_e32 vcc, v211, v210
	s_waitcnt lgkmcnt(3)
	v_mfma_f32_32x32x16_bf16 v[50:65], v[34:37], v[78:81], 0
	ds_read_b128 v[34:37], v124 offset:4608
	ds_read_b128 v[120:123], v124 offset:4624
	s_waitcnt lgkmcnt(4)
	v_mfma_f32_32x32x16_bf16 v[50:65], v[38:41], v[74:77], v[50:65]
	s_waitcnt lgkmcnt(3)
	v_mfma_f32_32x32x16_bf16 v[50:65], v[42:45], v[70:73], v[50:65]
	s_waitcnt lgkmcnt(2)
	v_mfma_f32_32x32x16_bf16 v[50:65], v[46:49], v[66:69], v[50:65]
	s_waitcnt lgkmcnt(1)
	v_mfma_f32_32x32x16_bf16 v[34:49], v[34:37], v[78:81], 0
	s_waitcnt lgkmcnt(0)
	v_mfma_f32_32x32x16_bf16 v[34:49], v[120:123], v[74:77], v[34:49]
	ds_read_b128 v[120:123], v124 offset:4640
	s_waitcnt lgkmcnt(0)
	v_mfma_f32_32x32x16_bf16 v[34:49], v[120:123], v[70:73], v[34:49]
	ds_read_b128 v[120:123], v124 offset:4656
	s_waitcnt lgkmcnt(0)
	v_mfma_f32_32x32x16_bf16 v[34:49], v[120:123], v[66:69], v[34:49]
	s_nop 1
	v_max3_f32 v120, v50, s85, v51
	v_max3_f32 v120, v120, v52, v53
	v_max3_f32 v120, v120, v54, v55
	v_max3_f32 v120, v120, v56, v57
	v_max3_f32 v120, v120, v58, v59
	v_max3_f32 v120, v120, v60, v61
	v_max3_f32 v120, v120, v62, v63
	v_max3_f32 v120, v120, v64, v65
	s_nop 1
	v_max3_f32 v120, v120, v34, v35
	v_max3_f32 v120, v120, v36, v37
	v_max3_f32 v120, v120, v38, v39
	v_max3_f32 v120, v120, v40, v41
	v_max3_f32 v120, v120, v42, v43
	v_max3_f32 v120, v120, v44, v45
	v_max3_f32 v120, v120, v46, v47
	v_cndmask_b32_e32 v121, v209, v211, vcc
	v_max3_f32 v120, v120, v48, v49
	v_mov_b32_e32 v121, v120
	s_nop 1
	v_permlane32_swap_b32_e32 v121, v120
	v_max_f32_e32 v120, v120, v121
	v_mul_f32_e32 v120, 0x3e38aa3b, v120
	v_cndmask_b32_e64 v120, v220, v120, s[74:75]
	v_add_f32_e32 v121, 0x40c00000, v119
	v_cmp_gt_f32_e32 vcc, v120, v121
	s_cbranch_vccz .LBB0_510
	s_nop 0
	v_cndmask_b32_e32 v121, v119, v120, vcc
	v_sub_f32_e32 v119, v119, v121
	v_exp_f32_e32 v119, v119
	s_nop 0
	v_cndmask_b32_e32 v120, 1.0, v119, vcc
	v_mul_f32_e32 v117, v117, v120
	v_pk_mul_f32 v[32:33], v[32:33], v[120:121] op_sel_hi:[1,0]
	v_pk_mul_f32 v[30:31], v[30:31], v[120:121] op_sel_hi:[1,0]
	v_pk_mul_f32 v[28:29], v[28:29], v[120:121] op_sel_hi:[1,0]
	v_pk_mul_f32 v[26:27], v[26:27], v[120:121] op_sel_hi:[1,0]
	v_pk_mul_f32 v[24:25], v[24:25], v[120:121] op_sel_hi:[1,0]
	v_pk_mul_f32 v[22:23], v[22:23], v[120:121] op_sel_hi:[1,0]
	v_pk_mul_f32 v[20:21], v[20:21], v[120:121] op_sel_hi:[1,0]
	v_pk_mul_f32 v[18:19], v[18:19], v[120:121] op_sel_hi:[1,0]
	v_pk_mul_f32 v[16:17], v[16:17], v[120:121] op_sel_hi:[1,0]
	v_pk_mul_f32 v[14:15], v[14:15], v[120:121] op_sel_hi:[1,0]
	v_pk_mul_f32 v[12:13], v[12:13], v[120:121] op_sel_hi:[1,0]
	v_pk_mul_f32 v[10:11], v[10:11], v[120:121] op_sel_hi:[1,0]
	v_pk_mul_f32 v[8:9], v[8:9], v[120:121] op_sel_hi:[1,0]
	v_pk_mul_f32 v[6:7], v[6:7], v[120:121] op_sel_hi:[1,0]
	v_pk_mul_f32 v[4:5], v[4:5], v[120:121] op_sel_hi:[1,0]
	v_pk_mul_f32 v[2:3], v[2:3], v[120:121] op_sel_hi:[1,0]
	v_mov_b32_e32 v119, v121

.LBB0_511:
	s_andn2_saveexec_b64 s[2:3], s[2:3]
	s_cbranch_execz .LBB0_515
	v_add3_u32 v124, s16, v100, v116
	s_setprio 1
	ds_read_b128 v[34:37], v124
	ds_read_b128 v[50:53], v124 offset:16
	ds_read_b128 v[54:57], v124 offset:32
	ds_read_b128 v[58:61], v124 offset:48
	v_cmp_lt_i32_e32 vcc, -1, v118
	s_waitcnt lgkmcnt(3)
	v_mfma_f32_32x32x16_bf16 v[34:49], v[34:37], v[78:81], 0
	v_cmp_gt_i32_e64 s[38:39], 1, v118
	v_cmp_gt_i32_e64 s[40:41], 32, v118
	v_cmp_gt_i32_e64 s[42:43], 33, v118
	v_cmp_gt_i32_e64 s[44:45], 34, v118
	v_cmp_gt_i32_e64 s[46:47], 35, v118
	v_cmp_gt_i32_e64 s[48:49], 36, v118
	v_cmp_gt_i32_e64 s[50:51], 37, v118
	s_waitcnt lgkmcnt(2)
	v_mfma_f32_32x32x16_bf16 v[34:49], v[50:53], v[74:77], v[34:49]
	ds_read_b128 v[50:53], v124 offset:4608
	ds_read_b128 v[120:123], v124 offset:4624
	v_cmp_gt_i32_e64 s[52:53], 38, v118
	v_cmp_gt_i32_e64 s[56:57], 39, v118
	v_cmp_gt_i32_e64 s[58:59], 48, v118
	v_cmp_gt_i32_e64 s[60:61], 49, v118
	v_cmp_gt_i32_e64 s[62:63], 50, v118
	s_waitcnt lgkmcnt(3)
	v_mfma_f32_32x32x16_bf16 v[34:49], v[54:57], v[70:73], v[34:49]
	v_cmp_gt_i32_e64 s[64:65], 51, v118
	v_cmp_gt_i32_e64 s[66:67], 52, v118
	v_cmp_gt_i32_e64 s[68:69], 53, v118
	v_cmp_gt_i32_e64 s[70:71], 54, v118
	v_cmp_gt_i32_e64 s[54:55], 55, v118
	s_waitcnt lgkmcnt(2)
	v_mfma_f32_32x32x16_bf16 v[34:49], v[58:61], v[66:69], v[34:49]
	s_waitcnt lgkmcnt(1)
	v_mfma_f32_32x32x16_bf16 v[50:65], v[50:53], v[78:81], 0
	s_waitcnt lgkmcnt(0)
	v_mfma_f32_32x32x16_bf16 v[50:65], v[120:123], v[74:77], v[50:65]
	ds_read_b128 v[120:123], v124 offset:4640
	s_waitcnt lgkmcnt(0)
	v_mfma_f32_32x32x16_bf16 v[50:65], v[120:123], v[70:73], v[50:65]
	ds_read_b128 v[120:123], v124 offset:4656
	s_waitcnt lgkmcnt(0)
	v_mfma_f32_32x32x16_bf16 v[50:65], v[120:123], v[66:69], v[50:65]
	s_nop 1
	v_cndmask_b32_e32 v122, v220, v34, vcc
	v_cmp_lt_i32_e32 vcc, 1, v118
	v_cndmask_b32_e64 v120, v35, v220, s[38:39]
	v_max3_f32 v35, v122, s85, v120
	v_cndmask_b32_e32 v36, v220, v36, vcc
	v_cmp_lt_i32_e32 vcc, 2, v118
	s_nop 3
	v_cndmask_b32_e64 v123, v50, v220, s[40:41]
	v_cndmask_b32_e32 v37, v220, v37, vcc
	v_cmp_lt_i32_e32 vcc, 3, v118
	v_max3_f32 v35, v35, v36, v37
	v_cndmask_b32_e64 v124, v51, v220, s[42:43]
	v_cndmask_b32_e32 v121, v220, v38, vcc
	v_cmp_lt_i32_e32 vcc, 4, v118
	v_cndmask_b32_e64 v125, v52, v220, s[44:45]
	v_cndmask_b32_e64 v126, v53, v220, s[46:47]
	v_cndmask_b32_e32 v38, v220, v39, vcc
	v_cmp_lt_i32_e32 vcc, 5, v118
	v_max3_f32 v35, v35, v121, v38
	v_cndmask_b32_e64 v127, v54, v220, s[48:49]
	v_cndmask_b32_e32 v39, v220, v40, vcc
	v_cmp_lt_i32_e32 vcc, 6, v118
	v_cndmask_b32_e64 v128, v55, v220, s[50:51]
	v_cndmask_b32_e64 v130, v56, v220, s[52:53]
	v_cndmask_b32_e32 v40, v220, v41, vcc
	v_cmp_lt_i32_e32 vcc, 15, v118
	v_max3_f32 v35, v35, v39, v40
	v_cndmask_b32_e64 v131, v57, v220, s[56:57]
	v_cndmask_b32_e32 v42, v220, v42, vcc
	v_cmp_lt_i32_e32 vcc, 16, v118
	v_cndmask_b32_e64 v132, v58, v220, s[58:59]
	v_cndmask_b32_e64 v133, v59, v220, s[60:61]
	v_cndmask_b32_e32 v41, v220, v43, vcc
	v_cmp_lt_i32_e32 vcc, 17, v118
	v_max3_f32 v35, v35, v42, v41
	v_cndmask_b32_e64 v134, v60, v220, s[62:63]
	v_cndmask_b32_e32 v43, v220, v44, vcc
	v_cmp_lt_i32_e32 vcc, 18, v118
	v_cndmask_b32_e64 v135, v61, v220, s[64:65]
	v_cndmask_b32_e64 v136, v62, v220, s[66:67]
	v_cndmask_b32_e32 v44, v220, v45, vcc
	v_cmp_lt_i32_e32 vcc, 19, v118
	v_max3_f32 v35, v35, v43, v44
	v_cndmask_b32_e64 v137, v63, v220, s[68:69]
	v_cndmask_b32_e32 v45, v220, v46, vcc
	v_cmp_lt_i32_e32 vcc, 20, v118
	v_cndmask_b32_e64 v129, v64, v220, s[70:71]
	s_nop 0
	v_cndmask_b32_e32 v46, v220, v47, vcc
	v_cmp_lt_i32_e32 vcc, 21, v118
	v_max3_f32 v35, v35, v45, v46
	s_nop 0
	v_cndmask_b32_e32 v47, v220, v48, vcc
	v_cmp_lt_i32_e32 vcc, 22, v118
	s_nop 1
	v_cndmask_b32_e32 v48, v220, v49, vcc
	v_max3_f32 v35, v35, v47, v48
	v_max3_f32 v35, v35, v123, v124
	v_max3_f32 v35, v35, v125, v126
	v_max3_f32 v35, v35, v127, v128
	v_max3_f32 v35, v35, v130, v131
	v_max3_f32 v35, v35, v132, v133
	v_max3_f32 v35, v35, v134, v135
	v_max3_f32 v138, v35, v136, v137
	v_cndmask_b32_e64 v35, v65, v220, s[54:55]
	v_cmp_lt_i32_e32 vcc, v211, v210
	v_max3_f32 v65, v138, v129, v35
	s_nop 0
	v_cndmask_b32_e32 v138, v209, v211, vcc
	v_mov_b32_e32 v138, v65
	s_nop 1
	v_permlane32_swap_b32_e32 v138, v65
	v_max_f32_e32 v65, v65, v138
	v_mul_f32_e32 v65, 0x3e38aa3b, v65
	v_add_f32_e32 v138, 0x40c00000, v119
	v_cmp_gt_f32_e32 vcc, v65, v138
	s_cbranch_vccz .LBB0_514
	s_nop 0
	v_cndmask_b32_e32 v65, v119, v65, vcc
	v_sub_f32_e32 v119, v119, v65
	v_exp_f32_e32 v119, v119
	s_nop 0
	v_cndmask_b32_e32 v138, 1.0, v119, vcc
	v_mul_f32_e32 v117, v117, v138
	v_pk_mul_f32 v[32:33], v[32:33], v[138:139] op_sel_hi:[1,0]
	v_pk_mul_f32 v[30:31], v[30:31], v[138:139] op_sel_hi:[1,0]
	v_pk_mul_f32 v[28:29], v[28:29], v[138:139] op_sel_hi:[1,0]
	v_pk_mul_f32 v[26:27], v[26:27], v[138:139] op_sel_hi:[1,0]
	v_pk_mul_f32 v[24:25], v[24:25], v[138:139] op_sel_hi:[1,0]
	v_pk_mul_f32 v[22:23], v[22:23], v[138:139] op_sel_hi:[1,0]
	v_pk_mul_f32 v[20:21], v[20:21], v[138:139] op_sel_hi:[1,0]
	v_pk_mul_f32 v[18:19], v[18:19], v[138:139] op_sel_hi:[1,0]
	v_pk_mul_f32 v[16:17], v[16:17], v[138:139] op_sel_hi:[1,0]
	v_pk_mul_f32 v[14:15], v[14:15], v[138:139] op_sel_hi:[1,0]
	v_pk_mul_f32 v[12:13], v[12:13], v[138:139] op_sel_hi:[1,0]
	v_pk_mul_f32 v[10:11], v[10:11], v[138:139] op_sel_hi:[1,0]
	v_pk_mul_f32 v[8:9], v[8:9], v[138:139] op_sel_hi:[1,0]
	v_pk_mul_f32 v[6:7], v[6:7], v[138:139] op_sel_hi:[1,0]
	v_pk_mul_f32 v[4:5], v[4:5], v[138:139] op_sel_hi:[1,0]
	v_pk_mul_f32 v[2:3], v[2:3], v[138:139] op_sel_hi:[1,0]
	v_mov_b32_e32 v119, v65

.LBB0_516:
	s_andn2_saveexec_b64 s[22:23], s[22:23]
	s_cbranch_execz .LBB0_522
	v_cmp_eq_u32_e32 vcc, 1, v34
	s_and_saveexec_b64 s[2:3], vcc
	s_cbranch_execz .LBB0_521
	v_add3_u32 v124, s16, v100, v116
	s_setprio 1
	ds_read_b128 v[34:37], v124
	ds_read_b128 v[38:41], v124 offset:16
	ds_read_b128 v[42:45], v124 offset:32
	ds_read_b128 v[46:49], v124 offset:48
	v_cmp_lt_i32_e32 vcc, v211, v210
	s_waitcnt lgkmcnt(3)
	v_mfma_f32_32x32x16_bf16 v[50:65], v[34:37], v[78:81], 0
	ds_read_b128 v[34:37], v124 offset:4608
	ds_read_b128 v[120:123], v124 offset:4624
	s_waitcnt lgkmcnt(4)
	v_mfma_f32_32x32x16_bf16 v[50:65], v[38:41], v[74:77], v[50:65]
	s_waitcnt lgkmcnt(3)
	v_mfma_f32_32x32x16_bf16 v[50:65], v[42:45], v[70:73], v[50:65]
	s_waitcnt lgkmcnt(2)
	v_mfma_f32_32x32x16_bf16 v[50:65], v[46:49], v[66:69], v[50:65]
	s_waitcnt lgkmcnt(1)
	v_mfma_f32_32x32x16_bf16 v[34:49], v[34:37], v[78:81], 0
	s_waitcnt lgkmcnt(0)
	v_mfma_f32_32x32x16_bf16 v[34:49], v[120:123], v[74:77], v[34:49]
	ds_read_b128 v[120:123], v124 offset:4640
	s_waitcnt lgkmcnt(0)
	v_mfma_f32_32x32x16_bf16 v[34:49], v[120:123], v[70:73], v[34:49]
	ds_read_b128 v[120:123], v124 offset:4656
	s_waitcnt lgkmcnt(0)
	v_mfma_f32_32x32x16_bf16 v[34:49], v[120:123], v[66:69], v[34:49]
	s_nop 1
	v_max3_f32 v120, v50, s85, v51
	v_max3_f32 v120, v120, v52, v53
	v_max3_f32 v120, v120, v54, v55
	v_max3_f32 v120, v120, v56, v57
	v_max3_f32 v120, v120, v58, v59
	v_max3_f32 v120, v120, v60, v61
	v_max3_f32 v120, v120, v62, v63
	v_max3_f32 v120, v120, v64, v65
	s_nop 1
	v_max3_f32 v120, v120, v34, v35
	v_max3_f32 v120, v120, v36, v37
	v_max3_f32 v120, v120, v38, v39
	v_max3_f32 v120, v120, v40, v41
	v_max3_f32 v120, v120, v42, v43
	v_max3_f32 v120, v120, v44, v45
	v_max3_f32 v120, v120, v46, v47
	v_cndmask_b32_e32 v121, v209, v211, vcc
	v_max3_f32 v120, v120, v48, v49
	v_mov_b32_e32 v121, v120
	s_nop 1
	v_permlane32_swap_b32_e32 v121, v120
	v_max_f32_e32 v120, v120, v121
	v_mul_f32_e32 v120, 0x3e38aa3b, v120
	v_add_f32_e32 v121, 0x40c00000, v119
	v_cmp_gt_f32_e32 vcc, v120, v121
	s_cbranch_vccz .LBB0_520
	s_nop 0
	v_cndmask_b32_e32 v121, v119, v120, vcc
	v_sub_f32_e32 v119, v119, v121
	v_exp_f32_e32 v119, v119
	s_nop 0
	v_cndmask_b32_e32 v120, 1.0, v119, vcc
	v_mul_f32_e32 v117, v117, v120
	v_pk_mul_f32 v[32:33], v[32:33], v[120:121] op_sel_hi:[1,0]
	v_pk_mul_f32 v[30:31], v[30:31], v[120:121] op_sel_hi:[1,0]
	v_pk_mul_f32 v[28:29], v[28:29], v[120:121] op_sel_hi:[1,0]
	v_pk_mul_f32 v[26:27], v[26:27], v[120:121] op_sel_hi:[1,0]
	v_pk_mul_f32 v[24:25], v[24:25], v[120:121] op_sel_hi:[1,0]
	v_pk_mul_f32 v[22:23], v[22:23], v[120:121] op_sel_hi:[1,0]
	v_pk_mul_f32 v[20:21], v[20:21], v[120:121] op_sel_hi:[1,0]
	v_pk_mul_f32 v[18:19], v[18:19], v[120:121] op_sel_hi:[1,0]
	v_pk_mul_f32 v[16:17], v[16:17], v[120:121] op_sel_hi:[1,0]
	v_pk_mul_f32 v[14:15], v[14:15], v[120:121] op_sel_hi:[1,0]
	v_pk_mul_f32 v[12:13], v[12:13], v[120:121] op_sel_hi:[1,0]
	v_pk_mul_f32 v[10:11], v[10:11], v[120:121] op_sel_hi:[1,0]
	v_pk_mul_f32 v[8:9], v[8:9], v[120:121] op_sel_hi:[1,0]
	v_pk_mul_f32 v[6:7], v[6:7], v[120:121] op_sel_hi:[1,0]
	v_pk_mul_f32 v[4:5], v[4:5], v[120:121] op_sel_hi:[1,0]
	v_pk_mul_f32 v[2:3], v[2:3], v[120:121] op_sel_hi:[1,0]
	v_mov_b32_e32 v119, v121

.LBB0_598:
	s_and_b64 vcc, exec, s[2:3]
	s_cbranch_vccz .LBB0_602
	s_nop 9
	v_add3_u32 v42, s37, v136, v139
	s_setprio 1
	ds_read_b128 v[34:37], v42
	ds_read_b128 v[38:41], v42 offset:16
	v_cmp_lt_i32_e32 vcc, v211, v210
	v_mov_b64_e32 v[64:65], v[16:17]
	v_mov_b32_e32 v153, v152
	s_waitcnt lgkmcnt(1)
	v_mfma_f32_32x32x16_bf16 v[82:97], v[34:37], v[98:101], 0
	v_mov_b32_e32 v154, v133
	v_mov_b64_e32 v[62:63], v[14:15]
	v_mov_b64_e32 v[60:61], v[12:13]
	v_mov_b64_e32 v[58:59], v[10:11]
	v_mov_b64_e32 v[56:57], v[8:9]
	v_mov_b64_e32 v[54:55], v[6:7]
	v_mov_b64_e32 v[52:53], v[4:5]
	s_waitcnt lgkmcnt(0)
	v_mfma_f32_32x32x16_bf16 v[82:97], v[38:41], v[102:105], v[82:97]
	ds_read_b128 v[34:37], v42 offset:32
	ds_read_b128 v[38:41], v42 offset:48
	v_mov_b64_e32 v[50:51], v[2:3]
	s_waitcnt lgkmcnt(1)
	v_mfma_f32_32x32x16_bf16 v[82:97], v[34:37], v[106:109], v[82:97]
	s_waitcnt lgkmcnt(0)
	v_mfma_f32_32x32x16_bf16 v[82:97], v[38:41], v[110:113], v[82:97]
	ds_read_b128 v[34:37], v42 offset:4608
	ds_read_b128 v[38:41], v42 offset:4624
	s_waitcnt lgkmcnt(1)
	v_mfma_f32_32x32x16_bf16 v[66:81], v[34:37], v[98:101], 0
	s_waitcnt lgkmcnt(0)
	v_mfma_f32_32x32x16_bf16 v[66:81], v[38:41], v[102:105], v[66:81]
	ds_read_b128 v[34:37], v42 offset:4640
	ds_read_b128 v[38:41], v42 offset:4656
	s_nop 3
	v_max3_f32 v42, v82, s85, v83
	s_waitcnt lgkmcnt(1)
	v_mfma_f32_32x32x16_bf16 v[66:81], v[34:37], v[106:109], v[66:81]
	v_max3_f32 v34, v42, v84, v85
	v_max3_f32 v34, v34, v86, v87
	v_max3_f32 v34, v34, v88, v89
	v_max3_f32 v34, v34, v90, v91
	v_max3_f32 v34, v34, v92, v93
	v_max3_f32 v34, v34, v94, v95
	v_max3_f32 v34, v34, v96, v97
	s_waitcnt lgkmcnt(0)
	v_mfma_f32_32x32x16_bf16 v[66:81], v[38:41], v[110:113], v[66:81]
	v_cndmask_b32_e32 v35, v209, v211, vcc
	v_lshlrev_b32_e32 v35, 2, v35
	v_add_f32_e32 v36, 0x40c00000, v152
	s_nop 8
	v_max3_f32 v34, v34, v66, v67
	v_max3_f32 v34, v34, v68, v69
	v_max3_f32 v34, v34, v70, v71
	v_max3_f32 v34, v34, v72, v73
	v_max3_f32 v34, v34, v74, v75
	v_max3_f32 v34, v34, v76, v77
	v_max3_f32 v34, v34, v78, v79
	v_max3_f32 v34, v34, v80, v81
	v_mov_b32_e32 v35, v34
	s_nop 1
	v_permlane32_swap_b32_e32 v35, v34
	v_max_f32_e32 v34, v34, v35
	v_mul_f32_e32 v155, 0x3e38aa3b, v34
	v_cmp_gt_f32_e32 vcc, v155, v36
	v_mov_b64_e32 v[48:49], v[32:33]
	v_mov_b64_e32 v[46:47], v[30:31]
	v_mov_b64_e32 v[44:45], v[28:29]
	v_mov_b64_e32 v[42:43], v[26:27]
	v_mov_b64_e32 v[40:41], v[24:25]
	v_mov_b64_e32 v[38:39], v[22:23]
	v_mov_b64_e32 v[36:37], v[20:21]
	v_mov_b64_e32 v[34:35], v[18:19]
	s_cbranch_vccz .LBB0_601
	v_cndmask_b32_e32 v153, v152, v155, vcc
	v_sub_f32_e32 v34, v152, v153
	v_exp_f32_e32 v34, v34
	s_nop 0
	v_cndmask_b32_e32 v34, 1.0, v34, vcc
	v_mul_f32_e32 v154, v133, v34
	v_pk_mul_f32 v[64:65], v[16:17], v[34:35] op_sel_hi:[1,0]
	v_pk_mul_f32 v[62:63], v[14:15], v[34:35] op_sel_hi:[1,0]
	v_pk_mul_f32 v[60:61], v[12:13], v[34:35] op_sel_hi:[1,0]
	v_pk_mul_f32 v[58:59], v[10:11], v[34:35] op_sel_hi:[1,0]
	v_pk_mul_f32 v[56:57], v[8:9], v[34:35] op_sel_hi:[1,0]
	v_pk_mul_f32 v[54:55], v[6:7], v[34:35] op_sel_hi:[1,0]
	v_pk_mul_f32 v[52:53], v[4:5], v[34:35] op_sel_hi:[1,0]
	v_pk_mul_f32 v[50:51], v[2:3], v[34:35] op_sel_hi:[1,0]
	v_pk_mul_f32 v[48:49], v[32:33], v[34:35] op_sel_hi:[1,0]
	v_pk_mul_f32 v[46:47], v[30:31], v[34:35] op_sel_hi:[1,0]
	v_pk_mul_f32 v[44:45], v[28:29], v[34:35] op_sel_hi:[1,0]
	v_pk_mul_f32 v[42:43], v[26:27], v[34:35] op_sel_hi:[1,0]
	v_pk_mul_f32 v[40:41], v[24:25], v[34:35] op_sel_hi:[1,0]
	v_pk_mul_f32 v[38:39], v[22:23], v[34:35] op_sel_hi:[1,0]
	v_pk_mul_f32 v[36:37], v[20:21], v[34:35] op_sel_hi:[1,0]
	v_pk_mul_f32 v[34:35], v[18:19], v[34:35] op_sel_hi:[1,0]

.LBB0_603:
	s_andn2_b64 vcc, exec, s[2:3]
	s_cbranch_vccnz .LBB0_614
	s_cmp_gt_i32 s76, 1
	s_mov_b64 s[2:3], -1
	s_cbranch_scc0 .LBB0_608
	s_nop 5
	v_add3_u32 v46, s37, v136, v139
	s_setprio 1
	ds_read_b128 v[34:37], v46
	ds_read_b128 v[38:41], v46 offset:16
	v_cmp_lt_i32_e32 vcc, -1, v151
	v_cmp_gt_i32_e64 s[38:39], 1, v151
	v_cmp_gt_i32_e64 s[40:41], 32, v151
	s_waitcnt lgkmcnt(1)
	v_mfma_f32_32x32x16_bf16 v[66:81], v[34:37], v[98:101], 0
	v_cmp_gt_i32_e64 s[42:43], 33, v151
	v_cmp_gt_i32_e64 s[44:45], 34, v151
	v_cmp_gt_i32_e64 s[46:47], 35, v151
	v_cmp_gt_i32_e64 s[48:49], 36, v151
	v_cmp_gt_i32_e64 s[50:51], 37, v151
	v_cmp_gt_i32_e64 s[52:53], 38, v151
	v_cmp_gt_i32_e64 s[56:57], 39, v151
	s_waitcnt lgkmcnt(0)
	v_mfma_f32_32x32x16_bf16 v[66:81], v[38:41], v[102:105], v[66:81]
	ds_read_b128 v[34:37], v46 offset:32
	ds_read_b128 v[38:41], v46 offset:48
	v_cmp_gt_i32_e64 s[58:59], 48, v151
	v_cmp_gt_i32_e64 s[60:61], 49, v151
	v_cmp_gt_i32_e64 s[62:63], 50, v151
	v_cmp_gt_i32_e64 s[64:65], 51, v151
	v_cmp_gt_i32_e64 s[66:67], 52, v151
	v_cmp_gt_i32_e64 s[68:69], 53, v151
	s_waitcnt lgkmcnt(1)
	v_mfma_f32_32x32x16_bf16 v[66:81], v[34:37], v[106:109], v[66:81]
	ds_read_b128 v[34:37], v46 offset:4608
	ds_read_b128 v[42:45], v46 offset:4624
	v_cmp_gt_i32_e64 s[70:71], 54, v151
	v_cmp_gt_i32_e64 s[54:55], 55, v151
	v_mov_b64_e32 v[64:65], v[16:17]
	v_mov_b32_e32 v153, v152
	v_mov_b64_e32 v[62:63], v[14:15]
	v_mov_b64_e32 v[60:61], v[12:13]
	s_waitcnt lgkmcnt(1)
	v_mfma_f32_32x32x16_bf16 v[82:97], v[34:37], v[98:101], 0
	ds_read_b128 v[34:37], v46 offset:4640
	ds_read_b128 v[46:49], v46 offset:4656
	v_mov_b64_e32 v[58:59], v[10:11]
	v_mov_b64_e32 v[56:57], v[8:9]
	v_mov_b64_e32 v[54:55], v[6:7]
	v_mov_b64_e32 v[52:53], v[4:5]
	v_mov_b64_e32 v[50:51], v[2:3]
	s_waitcnt lgkmcnt(2)
	v_mfma_f32_32x32x16_bf16 v[82:97], v[42:45], v[102:105], v[82:97]
	v_mfma_f32_32x32x16_bf16 v[66:81], v[38:41], v[110:113], v[66:81]
	s_waitcnt lgkmcnt(1)
	v_mfma_f32_32x32x16_bf16 v[82:97], v[34:37], v[106:109], v[82:97]
	s_nop 9
	v_cndmask_b32_e32 v158, v220, v66, vcc
	v_cmp_lt_i32_e32 vcc, 1, v151
	v_cndmask_b32_e64 v154, v67, v220, s[38:39]
	v_max3_f32 v38, v158, s85, v154
	v_cndmask_b32_e32 v155, v220, v68, vcc
	v_cmp_lt_i32_e32 vcc, 2, v151
	v_mov_b32_e32 v68, v133
	s_waitcnt lgkmcnt(0)
	v_mfma_f32_32x32x16_bf16 v[82:97], v[46:49], v[110:113], v[82:97]
	v_cndmask_b32_e32 v156, v220, v69, vcc
	v_cmp_lt_i32_e32 vcc, 3, v151
	v_max3_f32 v38, v38, v155, v156
	s_nop 0
	v_cndmask_b32_e32 v157, v220, v70, vcc
	v_cmp_lt_i32_e32 vcc, 4, v151
	s_nop 5
	v_cndmask_b32_e64 v159, v83, v220, s[42:43]
	v_cndmask_b32_e32 v69, v220, v71, vcc
	v_cmp_lt_i32_e32 vcc, 5, v151
	v_max3_f32 v38, v38, v157, v69
	v_cndmask_b32_e64 v160, v84, v220, s[44:45]
	v_cndmask_b32_e32 v70, v220, v72, vcc
	v_cmp_lt_i32_e32 vcc, 6, v151
	v_cndmask_b32_e64 v161, v85, v220, s[46:47]
	v_cndmask_b32_e64 v162, v86, v220, s[48:49]
	v_cndmask_b32_e32 v71, v220, v73, vcc
	v_cmp_lt_i32_e32 vcc, 15, v151
	v_max3_f32 v38, v38, v70, v71
	v_cndmask_b32_e64 v163, v87, v220, s[50:51]
	v_cndmask_b32_e32 v73, v220, v74, vcc
	v_cmp_lt_i32_e32 vcc, 16, v151
	v_cndmask_b32_e64 v165, v88, v220, s[52:53]
	v_cndmask_b32_e64 v166, v89, v220, s[56:57]
	v_cndmask_b32_e32 v72, v220, v75, vcc
	v_cmp_lt_i32_e32 vcc, 17, v151
	v_max3_f32 v38, v38, v73, v72
	v_cndmask_b32_e64 v167, v90, v220, s[58:59]
	v_cndmask_b32_e32 v74, v220, v76, vcc
	v_cmp_lt_i32_e32 vcc, 18, v151
	v_cndmask_b32_e64 v168, v91, v220, s[60:61]
	v_cndmask_b32_e64 v169, v92, v220, s[62:63]
	v_cndmask_b32_e32 v75, v220, v77, vcc
	v_cmp_lt_i32_e32 vcc, 19, v151
	v_max3_f32 v38, v38, v74, v75
	v_cndmask_b32_e64 v170, v93, v220, s[64:65]
	v_cndmask_b32_e32 v76, v220, v78, vcc
	v_cmp_lt_i32_e32 vcc, 20, v151
	v_cndmask_b32_e64 v171, v94, v220, s[66:67]
	v_cndmask_b32_e64 v172, v95, v220, s[68:69]
	v_cndmask_b32_e32 v77, v220, v79, vcc
	v_cmp_lt_i32_e32 vcc, 21, v151
	v_max3_f32 v34, v38, v76, v77
	v_cndmask_b32_e64 v164, v96, v220, s[70:71]
	v_cndmask_b32_e32 v78, v220, v80, vcc
	v_cmp_lt_i32_e32 vcc, 22, v151
	v_cndmask_b32_e64 v80, v82, v220, s[40:41]
	v_cndmask_b32_e64 v67, v97, v220, s[54:55]
	v_cndmask_b32_e32 v79, v220, v81, vcc
	v_max3_f32 v34, v34, v78, v79
	v_max3_f32 v34, v34, v80, v159
	v_max3_f32 v34, v34, v160, v161
	v_max3_f32 v34, v34, v162, v163
	v_max3_f32 v34, v34, v165, v166
	v_max3_f32 v34, v34, v167, v168
	v_max3_f32 v34, v34, v169, v170
	v_cmp_lt_i32_e32 vcc, v211, v210
	v_max3_f32 v34, v34, v171, v172
	v_max3_f32 v34, v34, v164, v67
	v_cndmask_b32_e32 v35, v209, v211, vcc
	v_mov_b32_e32 v35, v34
	s_nop 1
	v_permlane32_swap_b32_e32 v35, v34
	v_max_f32_e32 v34, v34, v35
	v_mul_f32_e32 v97, 0x3e38aa3b, v34
	v_add_f32_e32 v34, 0x40c00000, v152
	v_cmp_gt_f32_e32 vcc, v97, v34
	v_mov_b64_e32 v[48:49], v[32:33]
	v_mov_b64_e32 v[46:47], v[30:31]
	v_mov_b64_e32 v[44:45], v[28:29]
	v_mov_b64_e32 v[42:43], v[26:27]
	v_mov_b64_e32 v[40:41], v[24:25]
	v_mov_b64_e32 v[38:39], v[22:23]
	v_mov_b64_e32 v[36:37], v[20:21]
	v_mov_b64_e32 v[34:35], v[18:19]
	s_cbranch_vccz .LBB0_607
	v_cndmask_b32_e32 v153, v152, v97, vcc
	v_sub_f32_e32 v34, v152, v153
	v_exp_f32_e32 v34, v34
	s_nop 0
	v_cndmask_b32_e32 v34, 1.0, v34, vcc
	v_mul_f32_e32 v68, v133, v34
	v_pk_mul_f32 v[64:65], v[16:17], v[34:35] op_sel_hi:[1,0]
	v_pk_mul_f32 v[62:63], v[14:15], v[34:35] op_sel_hi:[1,0]
	v_pk_mul_f32 v[60:61], v[12:13], v[34:35] op_sel_hi:[1,0]
	v_pk_mul_f32 v[58:59], v[10:11], v[34:35] op_sel_hi:[1,0]
	v_pk_mul_f32 v[56:57], v[8:9], v[34:35] op_sel_hi:[1,0]
	v_pk_mul_f32 v[54:55], v[6:7], v[34:35] op_sel_hi:[1,0]
	v_pk_mul_f32 v[52:53], v[4:5], v[34:35] op_sel_hi:[1,0]
	v_pk_mul_f32 v[50:51], v[2:3], v[34:35] op_sel_hi:[1,0]
	v_pk_mul_f32 v[48:49], v[32:33], v[34:35] op_sel_hi:[1,0]
	v_pk_mul_f32 v[46:47], v[30:31], v[34:35] op_sel_hi:[1,0]
	v_pk_mul_f32 v[44:45], v[28:29], v[34:35] op_sel_hi:[1,0]
	v_pk_mul_f32 v[42:43], v[26:27], v[34:35] op_sel_hi:[1,0]
	v_pk_mul_f32 v[40:41], v[24:25], v[34:35] op_sel_hi:[1,0]
	v_pk_mul_f32 v[38:39], v[22:23], v[34:35] op_sel_hi:[1,0]
	v_pk_mul_f32 v[36:37], v[20:21], v[34:35] op_sel_hi:[1,0]
	v_pk_mul_f32 v[34:35], v[18:19], v[34:35] op_sel_hi:[1,0]

.LBB0_608:
	s_and_b64 vcc, exec, s[2:3]
	s_cbranch_vccz .LBB0_614
	s_cmp_lg_u32 s76, 1
	s_cbranch_scc1 .LBB0_613
	v_add3_u32 v70, s37, v136, v139
	s_nop 6
	s_setprio 1
	ds_read_b128 v[34:37], v70
	ds_read_b128 v[38:41], v70 offset:16
	ds_read_b128 v[42:45], v70 offset:32
	ds_read_b128 v[46:49], v70 offset:48
	v_cmp_lt_i32_e32 vcc, v211, v210
	s_waitcnt lgkmcnt(3)
	v_mfma_f32_32x32x16_bf16 v[50:65], v[34:37], v[98:101], 0
	ds_read_b128 v[34:37], v70 offset:4608
	ds_read_b128 v[66:69], v70 offset:4624
	s_waitcnt lgkmcnt(4)
	v_mfma_f32_32x32x16_bf16 v[50:65], v[38:41], v[102:105], v[50:65]
	s_waitcnt lgkmcnt(3)
	v_mfma_f32_32x32x16_bf16 v[50:65], v[42:45], v[106:109], v[50:65]
	s_waitcnt lgkmcnt(2)
	v_mfma_f32_32x32x16_bf16 v[50:65], v[46:49], v[110:113], v[50:65]
	s_waitcnt lgkmcnt(1)
	v_mfma_f32_32x32x16_bf16 v[34:49], v[34:37], v[98:101], 0
	s_waitcnt lgkmcnt(0)
	v_mfma_f32_32x32x16_bf16 v[34:49], v[66:69], v[102:105], v[34:49]
	ds_read_b128 v[66:69], v70 offset:4640
	s_waitcnt lgkmcnt(0)
	v_mfma_f32_32x32x16_bf16 v[34:49], v[66:69], v[106:109], v[34:49]
	ds_read_b128 v[66:69], v70 offset:4656
	s_waitcnt lgkmcnt(0)
	v_mfma_f32_32x32x16_bf16 v[34:49], v[66:69], v[110:113], v[34:49]
	s_nop 1
	v_max3_f32 v66, v50, s85, v51
	v_max3_f32 v66, v66, v52, v53
	v_max3_f32 v66, v66, v54, v55
	v_max3_f32 v66, v66, v56, v57
	v_max3_f32 v66, v66, v58, v59
	v_max3_f32 v66, v66, v60, v61
	v_max3_f32 v66, v66, v62, v63
	v_max3_f32 v66, v66, v64, v65
	s_nop 1
	v_max3_f32 v66, v66, v34, v35
	v_max3_f32 v66, v66, v36, v37
	v_max3_f32 v66, v66, v38, v39
	v_max3_f32 v66, v66, v40, v41
	v_max3_f32 v66, v66, v42, v43
	v_max3_f32 v66, v66, v44, v45
	v_max3_f32 v66, v66, v46, v47
	v_cndmask_b32_e32 v67, v209, v211, vcc
	v_max3_f32 v66, v66, v48, v49
	v_mov_b32_e32 v67, v66
	s_nop 1
	v_permlane32_swap_b32_e32 v67, v66
	v_max_f32_e32 v66, v66, v67
	v_mul_f32_e32 v66, 0x3e38aa3b, v66
	v_add_f32_e32 v67, 0x40c00000, v152
	v_cmp_gt_f32_e32 vcc, v66, v67
	s_cbranch_vccz .LBB0_612
	s_nop 0
	v_cndmask_b32_e32 v67, v152, v66, vcc
	v_sub_f32_e32 v66, v152, v67
	v_exp_f32_e32 v66, v66
	v_mov_b32_e32 v152, v67
	v_cndmask_b32_e32 v66, 1.0, v66, vcc
	v_mul_f32_e32 v133, v133, v66
	v_pk_mul_f32 v[16:17], v[16:17], v[66:67] op_sel_hi:[1,0]
	v_pk_mul_f32 v[14:15], v[14:15], v[66:67] op_sel_hi:[1,0]
	v_pk_mul_f32 v[12:13], v[12:13], v[66:67] op_sel_hi:[1,0]
	v_pk_mul_f32 v[10:11], v[10:11], v[66:67] op_sel_hi:[1,0]
	v_pk_mul_f32 v[8:9], v[8:9], v[66:67] op_sel_hi:[1,0]
	v_pk_mul_f32 v[6:7], v[6:7], v[66:67] op_sel_hi:[1,0]
	v_pk_mul_f32 v[4:5], v[4:5], v[66:67] op_sel_hi:[1,0]
	v_pk_mul_f32 v[2:3], v[2:3], v[66:67] op_sel_hi:[1,0]
	v_pk_mul_f32 v[32:33], v[32:33], v[66:67] op_sel_hi:[1,0]
	v_pk_mul_f32 v[30:31], v[30:31], v[66:67] op_sel_hi:[1,0]
	v_pk_mul_f32 v[28:29], v[28:29], v[66:67] op_sel_hi:[1,0]
	v_pk_mul_f32 v[26:27], v[26:27], v[66:67] op_sel_hi:[1,0]
	v_pk_mul_f32 v[24:25], v[24:25], v[66:67] op_sel_hi:[1,0]
	v_pk_mul_f32 v[22:23], v[22:23], v[66:67] op_sel_hi:[1,0]
	v_pk_mul_f32 v[20:21], v[20:21], v[66:67] op_sel_hi:[1,0]
	v_pk_mul_f32 v[18:19], v[18:19], v[66:67] op_sel_hi:[1,0]

.LBB0_757:
	s_andn2_b64 vcc, exec, s[2:3]
	s_cbranch_vccnz .LBB0_768
	s_cmp_gt_i32 s16, 1
	s_mov_b64 s[2:3], -1
	s_cbranch_scc0 .LBB0_762
	v_add3_u32 v46, s76, v132, v137
	s_setprio 1
	ds_read_b128 v[34:37], v46
	ds_read_b128 v[38:41], v46 offset:16
	v_cmp_lt_i32_e32 vcc, -1, v150
	v_cmp_gt_i32_e64 s[38:39], 1, v150
	v_cmp_gt_i32_e64 s[40:41], 32, v150
	s_waitcnt lgkmcnt(1)
	v_mfma_f32_32x32x16_bf16 v[66:81], v[34:37], v[98:101], 0
	v_cmp_gt_i32_e64 s[42:43], 33, v150
	v_cmp_gt_i32_e64 s[44:45], 34, v150
	v_cmp_gt_i32_e64 s[46:47], 35, v150
	v_cmp_gt_i32_e64 s[48:49], 36, v150
	v_cmp_gt_i32_e64 s[50:51], 37, v150
	v_cmp_gt_i32_e64 s[52:53], 38, v150
	v_cmp_gt_i32_e64 s[56:57], 39, v150
	s_waitcnt lgkmcnt(0)
	v_mfma_f32_32x32x16_bf16 v[66:81], v[38:41], v[102:105], v[66:81]
	ds_read_b128 v[34:37], v46 offset:32
	ds_read_b128 v[38:41], v46 offset:48
	v_cmp_gt_i32_e64 s[58:59], 48, v150
	v_cmp_gt_i32_e64 s[60:61], 49, v150
	v_cmp_gt_i32_e64 s[62:63], 50, v150
	v_cmp_gt_i32_e64 s[64:65], 51, v150
	v_cmp_gt_i32_e64 s[66:67], 52, v150
	v_cmp_gt_i32_e64 s[68:69], 53, v150
	s_waitcnt lgkmcnt(1)
	v_mfma_f32_32x32x16_bf16 v[66:81], v[34:37], v[106:109], v[66:81]
	ds_read_b128 v[34:37], v46 offset:4608
	ds_read_b128 v[42:45], v46 offset:4624
	v_cmp_gt_i32_e64 s[70:71], 54, v150
	v_cmp_gt_i32_e64 s[54:55], 55, v150
	v_mov_b64_e32 v[64:65], v[32:33]
	v_mov_b32_e32 v153, v152
	v_mov_b64_e32 v[62:63], v[30:31]
	v_mov_b64_e32 v[60:61], v[28:29]
	s_waitcnt lgkmcnt(1)
	v_mfma_f32_32x32x16_bf16 v[82:97], v[34:37], v[98:101], 0
	ds_read_b128 v[34:37], v46 offset:4640
	ds_read_b128 v[46:49], v46 offset:4656
	v_mov_b64_e32 v[58:59], v[26:27]
	v_mov_b64_e32 v[56:57], v[24:25]
	v_mov_b64_e32 v[54:55], v[22:23]
	v_mov_b64_e32 v[52:53], v[20:21]
	v_mov_b64_e32 v[50:51], v[18:19]
	s_waitcnt lgkmcnt(2)
	v_mfma_f32_32x32x16_bf16 v[82:97], v[42:45], v[102:105], v[82:97]
	v_mfma_f32_32x32x16_bf16 v[66:81], v[38:41], v[110:113], v[66:81]
	s_waitcnt lgkmcnt(1)
	v_mfma_f32_32x32x16_bf16 v[82:97], v[34:37], v[106:109], v[82:97]
	s_nop 9
	v_cndmask_b32_e32 v158, v220, v66, vcc
	v_cmp_lt_i32_e32 vcc, 1, v150
	v_cndmask_b32_e64 v154, v67, v220, s[38:39]
	v_max3_f32 v38, v158, s85, v154
	v_cndmask_b32_e32 v155, v220, v68, vcc
	v_cmp_lt_i32_e32 vcc, 2, v150
	v_mov_b32_e32 v68, v151
	s_waitcnt lgkmcnt(0)
	v_mfma_f32_32x32x16_bf16 v[82:97], v[46:49], v[110:113], v[82:97]
	v_cndmask_b32_e32 v156, v220, v69, vcc
	v_cmp_lt_i32_e32 vcc, 3, v150
	v_max3_f32 v38, v38, v155, v156
	s_nop 0
	v_cndmask_b32_e32 v157, v220, v70, vcc
	v_cmp_lt_i32_e32 vcc, 4, v150
	s_nop 5
	v_cndmask_b32_e64 v159, v83, v220, s[42:43]
	v_cndmask_b32_e32 v69, v220, v71, vcc
	v_cmp_lt_i32_e32 vcc, 5, v150
	v_max3_f32 v38, v38, v157, v69
	v_cndmask_b32_e64 v160, v84, v220, s[44:45]
	v_cndmask_b32_e32 v70, v220, v72, vcc
	v_cmp_lt_i32_e32 vcc, 6, v150
	v_cndmask_b32_e64 v161, v85, v220, s[46:47]
	v_cndmask_b32_e64 v162, v86, v220, s[48:49]
	v_cndmask_b32_e32 v71, v220, v73, vcc
	v_cmp_lt_i32_e32 vcc, 15, v150
	v_max3_f32 v38, v38, v70, v71
	v_cndmask_b32_e64 v163, v87, v220, s[50:51]
	v_cndmask_b32_e32 v73, v220, v74, vcc
	v_cmp_lt_i32_e32 vcc, 16, v150
	v_cndmask_b32_e64 v165, v88, v220, s[52:53]
	v_cndmask_b32_e64 v166, v89, v220, s[56:57]
	v_cndmask_b32_e32 v72, v220, v75, vcc
	v_cmp_lt_i32_e32 vcc, 17, v150
	v_max3_f32 v38, v38, v73, v72
	v_cndmask_b32_e64 v167, v90, v220, s[58:59]
	v_cndmask_b32_e32 v74, v220, v76, vcc
	v_cmp_lt_i32_e32 vcc, 18, v150
	v_cndmask_b32_e64 v168, v91, v220, s[60:61]
	v_cndmask_b32_e64 v169, v92, v220, s[62:63]
	v_cndmask_b32_e32 v75, v220, v77, vcc
	v_cmp_lt_i32_e32 vcc, 19, v150
	v_max3_f32 v38, v38, v74, v75
	v_cndmask_b32_e64 v170, v93, v220, s[64:65]
	v_cndmask_b32_e32 v76, v220, v78, vcc
	v_cmp_lt_i32_e32 vcc, 20, v150
	v_cndmask_b32_e64 v171, v94, v220, s[66:67]
	v_cndmask_b32_e64 v172, v95, v220, s[68:69]
	v_cndmask_b32_e32 v77, v220, v79, vcc
	v_cmp_lt_i32_e32 vcc, 21, v150
	v_max3_f32 v34, v38, v76, v77
	v_cndmask_b32_e64 v164, v96, v220, s[70:71]
	v_cndmask_b32_e32 v78, v220, v80, vcc
	v_cmp_lt_i32_e32 vcc, 22, v150
	v_cndmask_b32_e64 v80, v82, v220, s[40:41]
	v_cndmask_b32_e64 v67, v97, v220, s[54:55]
	v_cndmask_b32_e32 v79, v220, v81, vcc
	v_max3_f32 v34, v34, v78, v79
	v_max3_f32 v34, v34, v80, v159
	v_max3_f32 v34, v34, v160, v161
	v_max3_f32 v34, v34, v162, v163
	v_max3_f32 v34, v34, v165, v166
	v_max3_f32 v34, v34, v167, v168
	v_max3_f32 v34, v34, v169, v170
	v_cmp_lt_i32_e32 vcc, v211, v210
	v_max3_f32 v34, v34, v171, v172
	v_max3_f32 v34, v34, v164, v67
	v_cndmask_b32_e32 v35, v209, v211, vcc
	v_mov_b32_e32 v35, v34
	s_nop 1
	v_permlane32_swap_b32_e32 v35, v34
	v_max_f32_e32 v34, v34, v35
	v_mul_f32_e32 v97, 0x3e38aa3b, v34
	v_add_f32_e32 v34, 0x40c00000, v152
	v_cmp_gt_f32_e32 vcc, v97, v34
	v_mov_b64_e32 v[48:49], v[16:17]
	v_mov_b64_e32 v[46:47], v[14:15]
	v_mov_b64_e32 v[44:45], v[12:13]
	v_mov_b64_e32 v[42:43], v[10:11]
	v_mov_b64_e32 v[40:41], v[8:9]
	v_mov_b64_e32 v[38:39], v[6:7]
	v_mov_b64_e32 v[36:37], v[4:5]
	v_mov_b64_e32 v[34:35], v[2:3]
	s_cbranch_vccz .LBB0_761
	v_cndmask_b32_e32 v153, v152, v97, vcc
	v_sub_f32_e32 v34, v152, v153
	v_exp_f32_e32 v34, v34
	s_nop 0
	v_cndmask_b32_e32 v50, 1.0, v34, vcc
	v_mul_f32_e32 v68, v151, v50
	v_pk_mul_f32 v[48:49], v[16:17], v[50:51] op_sel_hi:[1,0]
	v_pk_mul_f32 v[46:47], v[14:15], v[50:51] op_sel_hi:[1,0]
	v_pk_mul_f32 v[44:45], v[12:13], v[50:51] op_sel_hi:[1,0]
	v_pk_mul_f32 v[42:43], v[10:11], v[50:51] op_sel_hi:[1,0]
	v_pk_mul_f32 v[40:41], v[8:9], v[50:51] op_sel_hi:[1,0]
	v_pk_mul_f32 v[38:39], v[6:7], v[50:51] op_sel_hi:[1,0]
	v_pk_mul_f32 v[36:37], v[4:5], v[50:51] op_sel_hi:[1,0]
	v_pk_mul_f32 v[34:35], v[2:3], v[50:51] op_sel_hi:[1,0]
	v_pk_mul_f32 v[64:65], v[32:33], v[50:51] op_sel_hi:[1,0]
	v_pk_mul_f32 v[62:63], v[30:31], v[50:51] op_sel_hi:[1,0]
	v_pk_mul_f32 v[60:61], v[28:29], v[50:51] op_sel_hi:[1,0]
	v_pk_mul_f32 v[58:59], v[26:27], v[50:51] op_sel_hi:[1,0]
	v_pk_mul_f32 v[56:57], v[24:25], v[50:51] op_sel_hi:[1,0]
	v_pk_mul_f32 v[54:55], v[22:23], v[50:51] op_sel_hi:[1,0]
	v_pk_mul_f32 v[52:53], v[20:21], v[50:51] op_sel_hi:[1,0]
	v_pk_mul_f32 v[50:51], v[18:19], v[50:51] op_sel_hi:[1,0]

.LBB0_762:
	s_and_b64 vcc, exec, s[2:3]
	s_cbranch_vccz .LBB0_768
	s_cmp_lg_u32 s16, 1
	s_cbranch_scc1 .LBB0_767
	v_add3_u32 v70, s76, v132, v137
	s_setprio 1
	ds_read_b128 v[34:37], v70
	ds_read_b128 v[38:41], v70 offset:16
	ds_read_b128 v[42:45], v70 offset:32
	ds_read_b128 v[46:49], v70 offset:48
	v_cmp_lt_i32_e32 vcc, v211, v210
	s_waitcnt lgkmcnt(3)
	v_mfma_f32_32x32x16_bf16 v[50:65], v[34:37], v[98:101], 0
	ds_read_b128 v[34:37], v70 offset:4608
	ds_read_b128 v[66:69], v70 offset:4624
	s_waitcnt lgkmcnt(4)
	v_mfma_f32_32x32x16_bf16 v[50:65], v[38:41], v[102:105], v[50:65]
	s_waitcnt lgkmcnt(3)
	v_mfma_f32_32x32x16_bf16 v[50:65], v[42:45], v[106:109], v[50:65]
	s_waitcnt lgkmcnt(2)
	v_mfma_f32_32x32x16_bf16 v[50:65], v[46:49], v[110:113], v[50:65]
	s_waitcnt lgkmcnt(1)
	v_mfma_f32_32x32x16_bf16 v[34:49], v[34:37], v[98:101], 0
	s_waitcnt lgkmcnt(0)
	v_mfma_f32_32x32x16_bf16 v[34:49], v[66:69], v[102:105], v[34:49]
	ds_read_b128 v[66:69], v70 offset:4640
	s_waitcnt lgkmcnt(0)
	v_mfma_f32_32x32x16_bf16 v[34:49], v[66:69], v[106:109], v[34:49]
	ds_read_b128 v[66:69], v70 offset:4656
	s_waitcnt lgkmcnt(0)
	v_mfma_f32_32x32x16_bf16 v[34:49], v[66:69], v[110:113], v[34:49]
	s_nop 1
	v_max3_f32 v66, v50, s85, v51
	v_max3_f32 v66, v66, v52, v53
	v_max3_f32 v66, v66, v54, v55
	v_max3_f32 v66, v66, v56, v57
	v_max3_f32 v66, v66, v58, v59
	v_max3_f32 v66, v66, v60, v61
	v_max3_f32 v66, v66, v62, v63
	v_max3_f32 v66, v66, v64, v65
	s_nop 1
	v_max3_f32 v66, v66, v34, v35
	v_max3_f32 v66, v66, v36, v37
	v_max3_f32 v66, v66, v38, v39
	v_max3_f32 v66, v66, v40, v41
	v_max3_f32 v66, v66, v42, v43
	v_max3_f32 v66, v66, v44, v45
	v_max3_f32 v66, v66, v46, v47
	v_cndmask_b32_e32 v67, v209, v211, vcc
	v_max3_f32 v66, v66, v48, v49
	v_mov_b32_e32 v67, v66
	s_nop 1
	v_permlane32_swap_b32_e32 v67, v66
	v_max_f32_e32 v66, v66, v67
	v_mul_f32_e32 v66, 0x3e38aa3b, v66
	v_add_f32_e32 v67, 0x40c00000, v152
	v_cmp_gt_f32_e32 vcc, v66, v67
	s_cbranch_vccz .LBB0_766
	s_nop 0
	v_cndmask_b32_e32 v67, v152, v66, vcc
	v_sub_f32_e32 v66, v152, v67
	v_exp_f32_e32 v66, v66
	v_mov_b32_e32 v152, v67
	v_cndmask_b32_e32 v66, 1.0, v66, vcc
	v_mul_f32_e32 v151, v151, v66
	v_pk_mul_f32 v[16:17], v[16:17], v[66:67] op_sel_hi:[1,0]
	v_pk_mul_f32 v[14:15], v[14:15], v[66:67] op_sel_hi:[1,0]
	v_pk_mul_f32 v[12:13], v[12:13], v[66:67] op_sel_hi:[1,0]
	v_pk_mul_f32 v[10:11], v[10:11], v[66:67] op_sel_hi:[1,0]
	v_pk_mul_f32 v[8:9], v[8:9], v[66:67] op_sel_hi:[1,0]
	v_pk_mul_f32 v[6:7], v[6:7], v[66:67] op_sel_hi:[1,0]
	v_pk_mul_f32 v[4:5], v[4:5], v[66:67] op_sel_hi:[1,0]
	v_pk_mul_f32 v[2:3], v[2:3], v[66:67] op_sel_hi:[1,0]
	v_pk_mul_f32 v[32:33], v[32:33], v[66:67] op_sel_hi:[1,0]
	v_pk_mul_f32 v[30:31], v[30:31], v[66:67] op_sel_hi:[1,0]
	v_pk_mul_f32 v[28:29], v[28:29], v[66:67] op_sel_hi:[1,0]
	v_pk_mul_f32 v[26:27], v[26:27], v[66:67] op_sel_hi:[1,0]
	v_pk_mul_f32 v[24:25], v[24:25], v[66:67] op_sel_hi:[1,0]
	v_pk_mul_f32 v[22:23], v[22:23], v[66:67] op_sel_hi:[1,0]
	v_pk_mul_f32 v[20:21], v[20:21], v[66:67] op_sel_hi:[1,0]
	v_pk_mul_f32 v[18:19], v[18:19], v[66:67] op_sel_hi:[1,0]
